# speedup vs baseline: 1.0116x; 1.0008x over previous
; __device__ __forceinline__ void partialSM(f32x16& p0, f32x16& p1, float& m_reg, float& mn, float& alpha) {
;     ...
;     const float mnL = -mn * C2;
; #pragma unroll
;     for (int r = 0; r < 16; ++r) p0[r] = fmaf(p0[r], C2, mnL);
; #pragma unroll
;     for (int r = 0; r < 16; ++r) p1[r] = fmaf(p1[r], C2, mnL);
.LBB0_414:
	v_mul_f32_e32 v181, 0xbdd53b94, v210
	v_pk_fma_f32 v[240:241], v[66:67], s[84:85], v[180:181] op_sel:[0,0,1] op_sel_hi:[1,0,1]
	v_pk_fma_f32 v[222:223], v[68:69], s[84:85], v[180:181] op_sel:[0,0,1] op_sel_hi:[1,0,1]
	v_pk_fma_f32 v[216:217], v[70:71], s[84:85], v[180:181] op_sel:[0,0,1] op_sel_hi:[1,0,1]
	v_pk_fma_f32 v[218:219], v[72:73], s[84:85], v[180:181] op_sel:[0,0,1] op_sel_hi:[1,0,1]
	v_pk_fma_f32 v[220:221], v[74:75], s[84:85], v[180:181] op_sel:[0,0,1] op_sel_hi:[1,0,1]
	v_pk_fma_f32 v[238:239], v[76:77], s[84:85], v[180:181] op_sel:[0,0,1] op_sel_hi:[1,0,1]
	v_pk_fma_f32 v[226:227], v[78:79], s[84:85], v[180:181] op_sel:[0,0,1] op_sel_hi:[1,0,1]
	v_pk_fma_f32 v[228:229], v[80:81], s[84:85], v[180:181] op_sel:[0,0,1] op_sel_hi:[1,0,1]
	v_pk_fma_f32 v[166:167], v[82:83], s[84:85], v[180:181] op_sel:[0,0,1] op_sel_hi:[1,0,1]
	v_pk_fma_f32 v[168:169], v[84:85], s[84:85], v[180:181] op_sel:[0,0,1] op_sel_hi:[1,0,1]
	v_pk_fma_f32 v[170:171], v[86:87], s[84:85], v[180:181] op_sel:[0,0,1] op_sel_hi:[1,0,1]
	v_pk_fma_f32 v[172:173], v[88:89], s[84:85], v[180:181] op_sel:[0,0,1] op_sel_hi:[1,0,1]
	v_pk_fma_f32 v[174:175], v[90:91], s[84:85], v[180:181] op_sel:[0,0,1] op_sel_hi:[1,0,1]
	v_pk_fma_f32 v[176:177], v[92:93], s[84:85], v[180:181] op_sel:[0,0,1] op_sel_hi:[1,0,1]
	v_pk_fma_f32 v[178:179], v[94:95], s[84:85], v[180:181] op_sel:[0,0,1] op_sel_hi:[1,0,1]
	v_pk_fma_f32 v[180:181], v[96:97], s[84:85], v[180:181] op_sel:[0,0,1] op_sel_hi:[1,0,1]
	s_waitcnt lgkmcnt(0)
	s_barrier
; __device__ __forceinline__ void finishSM(f32x16& p0, f32x16& p1, float alpha, float& l_reg, bf16x8& pa0, bf16x8& pa1, bf16x8& pa2, bf16x8& pa3) {
; #pragma unroll
;     for (int r = 0; r < 16; ++r) p1[r] = __builtin_amdgcn_exp2f(p1[r]);
;     float ps = 0;
; #pragma unroll
;     for (int r = 0; r < 16; ++r) ps += p0[r];
; #pragma unroll
;     for (int r = 0; r < 16; ++r) ps += p1[r];
;     { auto rr = __builtin_amdgcn_permlane32_swap(__float_as_uint(ps), __float_as_uint(ps), false, false);
;       ps = __uint_as_float(rr[0]) + __uint_as_float(rr[1]); }
;     l_reg = l_reg * alpha + ps;
;     ...
;     PK4(p0, 0, pa0); PK4(p0, 8, pa1); PK4(p1, 0, pa2); PK4(p1, 8, pa3);
;     ...
; }
; template <int KB>
; __device__ __forceinline__ void qkt(f32x16& p0, f32x16& p1, const char* lds, int r32, int hi, const bf16x8* qr) {
;     p0 = f32x16{}; p1 = f32x16{};
;     const char* kb = lds + AO_K + KB * SHM_K + KSWZ(r32, hi * 16); const char* rb = lds + AO_R + KB * SHM_R + RSWZ(r32, hi * 16);
; #pragma unroll
;     for (int d0 = 0; d0 < 8; ++d0) { const char* a = kb + d0 * 32;
;         bf16x8 b0 = *reinterpret_cast<const bf16x8*>(a);
;         bf16x8 b1 = *reinterpret_cast<const bf16x8*>(a + 32 * KPITCH);
;         p0 = __builtin_amdgcn_mfma_f32_32x32x16_bf16(b0, qr[d0], p0, 0, 0, 0);
;         p1 = __builtin_amdgcn_mfma_f32_32x32x16_bf16(b1, qr[d0], p1, 0, 0, 0); }
; #pragma unroll
;     for (int d0 = 0; d0 < 4; ++d0) { const char* a = rb + d0 * 32;
;         bf16x8 b0 = *reinterpret_cast<const bf16x8*>(a);
;         bf16x8 b1 = *reinterpret_cast<const bf16x8*>(a + 32 * RPITCH);
;         p0 = __builtin_amdgcn_mfma_f32_32x32x16_bf16(b0, qr[8 + d0], p0, 0, 0, 0);
;         p1 = __builtin_amdgcn_mfma_f32_32x32x16_bf16(b1, qr[8 + d0], p1, 0, 0, 0); }
	ds_read_b128 v[70:73], v200 offset:32768
	ds_read_b128 v[66:69], v200 offset:41472
	ds_read_b128 v[230:233], v200 offset:32800
	ds_read_b128 v[234:237], v200 offset:41504
	ds_read_b128 v[242:245], v200 offset:32832
	ds_read_b128 v[246:249], v200 offset:41536
	v_exp_f32_e32 v166, v166
	v_exp_f32_e32 v167, v167
	v_exp_f32_e32 v168, v168
	v_exp_f32_e32 v169, v169
	s_waitcnt lgkmcnt(4)
	v_mfma_f32_32x32x16_bf16 v[82:97], v[70:73], v[142:145], 0
	v_exp_f32_e32 v170, v170
	v_exp_f32_e32 v171, v171
	v_exp_f32_e32 v172, v172
	v_exp_f32_e32 v173, v173
	v_mfma_f32_32x32x16_bf16 v[66:81], v[66:69], v[142:145], 0
	v_exp_f32_e32 v174, v174
	v_exp_f32_e32 v175, v175
	v_exp_f32_e32 v176, v176
	v_exp_f32_e32 v177, v177
	s_waitcnt lgkmcnt(2)
	v_mfma_f32_32x32x16_bf16 v[66:81], v[234:237], v[138:141], v[66:81]
	v_exp_f32_e32 v178, v178
	v_exp_f32_e32 v179, v179
	v_exp_f32_e32 v180, v180
	v_exp_f32_e32 v181, v181
	v_mfma_f32_32x32x16_bf16 v[82:97], v[230:233], v[138:141], v[82:97]
	ds_read_b128 v[230:233], v200 offset:32864
	ds_read_b128 v[234:237], v200 offset:41568
	v_exp_f32_e32 v192, v222
	v_exp_f32_e32 v225, v226
	v_add_f32_e32 v215, v167, v166
	s_waitcnt lgkmcnt(2)
	v_mfma_f32_32x32x16_bf16 v[66:81], v[246:249], v[134:137], v[66:81]
	v_add_f32_e32 v215, v168, v215
	v_add_f32_e32 v215, v169, v215
	v_add_f32_e32 v215, v170, v215
	v_add_f32_e32 v215, v171, v215
	v_mfma_f32_32x32x16_bf16 v[82:97], v[242:245], v[134:137], v[82:97]
	ds_read_b128 v[242:245], v200 offset:32896
	ds_read_b128 v[246:249], v200 offset:41600
	v_add_f32_e32 v215, v172, v215
	v_add_f32_e32 v215, v173, v215
	v_add_f32_e32 v215, v174, v215
	v_add_f32_e32 v215, v175, v215
	s_waitcnt lgkmcnt(2)
	v_mfma_f32_32x32x16_bf16 v[66:81], v[234:237], v[130:133], v[66:81]
	v_add_f32_e32 v215, v176, v215
	v_add_f32_e32 v215, v177, v215
	v_exp_f32_e32 v190, v240
	v_add_f32_e32 v215, v178, v215
	v_mfma_f32_32x32x16_bf16 v[82:97], v[230:233], v[130:133], v[82:97]
	ds_read_b128 v[230:233], v200 offset:32928
	ds_read_b128 v[234:237], v200 offset:41632
	v_exp_f32_e32 v191, v241
	v_add_f32_e32 v215, v179, v215
	v_add_f32_e32 v215, v180, v215
	v_exp_f32_e32 v193, v223
	s_waitcnt lgkmcnt(2)
	v_mfma_f32_32x32x16_bf16 v[66:81], v[246:249], v[126:129], v[66:81]
	v_add_f32_e32 v215, v181, v215
	v_exp_f32_e32 v223, v216
	v_add_f32_e32 v215, v190, v215
	v_exp_f32_e32 v224, v217
	v_mfma_f32_32x32x16_bf16 v[82:97], v[242:245], v[126:129], v[82:97]
	ds_read_b128 v[242:245], v200 offset:32960
	ds_read_b128 v[246:249], v200 offset:41664
	v_add_f32_e32 v215, v191, v215
	v_exp_f32_e32 v217, v218
	v_add_f32_e32 v215, v192, v215
	v_exp_f32_e32 v218, v219
	s_waitcnt lgkmcnt(2)
	v_mfma_f32_32x32x16_bf16 v[66:81], v[234:237], v[122:125], v[66:81]
	v_add_f32_e32 v215, v193, v215
	v_exp_f32_e32 v219, v220
	v_add_f32_e32 v215, v223, v215
	v_mfma_f32_32x32x16_bf16 v[82:97], v[230:233], v[122:125], v[82:97]
	ds_read_b128 v[230:233], v200 offset:32992
	ds_read_b128 v[234:237], v200 offset:41696
	v_exp_f32_e32 v220, v221
	v_add_f32_e32 v215, v224, v215
	v_exp_f32_e32 v221, v238
	v_add_f32_e32 v215, v217, v215
	s_waitcnt lgkmcnt(2)
	v_mfma_f32_32x32x16_bf16 v[66:81], v[246:249], v[118:121], v[66:81]
	v_exp_f32_e32 v222, v239
	v_add_f32_e32 v215, v218, v215
	v_add_f32_e32 v215, v219, v215
	v_exp_f32_e32 v226, v227
	v_mfma_f32_32x32x16_bf16 v[82:97], v[242:245], v[118:121], v[82:97]
	ds_read_b128 v[242:245], v204
	ds_read_b128 v[246:249], v204 offset:4608
	v_add_f32_e32 v215, v220, v215
	v_exp_f32_e32 v227, v228
	v_add_f32_e32 v215, v221, v215
	v_exp_f32_e32 v214, v229
	s_waitcnt lgkmcnt(2)
	v_mfma_f32_32x32x16_bf16 v[66:81], v[234:237], v[110:113], v[66:81]
	v_add_f32_e32 v215, v222, v215
	v_add_f32_e32 v215, v225, v215
	v_add_f32_e32 v215, v226, v215
	v_add_f32_e32 v215, v227, v215
	v_mfma_f32_32x32x16_bf16 v[82:97], v[230:233], v[110:113], v[82:97]
	ds_read_b128 v[230:233], v204 offset:32
	ds_read_b128 v[234:237], v204 offset:4640
	v_add_f32_e32 v215, v214, v215
	v_mov_b32_e32 v216, v215
	v_cvt_pk_bf16_f32 v166, v166, v167
	v_cvt_pk_bf16_f32 v167, v168, v169
	s_waitcnt lgkmcnt(2)
	v_mfma_f32_32x32x16_bf16 v[66:81], v[246:249], v[114:117], v[66:81]
	v_cvt_pk_bf16_f32 v168, v170, v171
	v_cvt_pk_bf16_f32 v169, v172, v173
	v_cvt_pk_bf16_f32 v170, v174, v175
	v_cvt_pk_bf16_f32 v171, v176, v177
	v_mfma_f32_32x32x16_bf16 v[82:97], v[242:245], v[114:117], v[82:97]
	ds_read_b128 v[242:245], v204 offset:64
	ds_read_b128 v[246:249], v204 offset:4672
	v_cvt_pk_bf16_f32 v172, v178, v179
	v_cvt_pk_bf16_f32 v173, v180, v181
	v_cvt_pk_bf16_f32 v174, v190, v191
	v_cvt_pk_bf16_f32 v175, v192, v193
	s_waitcnt lgkmcnt(2)
	v_mfma_f32_32x32x16_bf16 v[82:97], v[230:233], v[106:109], v[82:97]
	v_cvt_pk_bf16_f32 v176, v223, v224
	v_cvt_pk_bf16_f32 v177, v217, v218
	v_cvt_pk_bf16_f32 v178, v219, v220
	v_cvt_pk_bf16_f32 v179, v221, v222
	v_mfma_f32_32x32x16_bf16 v[66:81], v[234:237], v[106:109], v[66:81]
	ds_read_b128 v[230:233], v204 offset:96
	ds_read_b128 v[234:237], v204 offset:4704
	v_cvt_pk_bf16_f32 v180, v225, v226
	v_cvt_pk_bf16_f32 v181, v227, v214
	v_permlane32_swap_b32_e32 v215, v216
	v_permlane32_swap_b32_e32 v166, v168
	s_waitcnt lgkmcnt(2)
	v_mfma_f32_32x32x16_bf16 v[82:97], v[242:245], v[102:105], v[82:97]
	v_permlane32_swap_b32_e32 v167, v169
	v_permlane32_swap_b32_e32 v170, v172
	v_permlane32_swap_b32_e32 v171, v173
	v_permlane32_swap_b32_e32 v174, v176
	v_mfma_f32_32x32x16_bf16 v[66:81], v[246:249], v[102:105], v[66:81]
	v_permlane32_swap_b32_e32 v175, v177
	v_permlane32_swap_b32_e32 v178, v180
	v_permlane32_swap_b32_e32 v179, v181
	s_waitcnt lgkmcnt(0)
	v_mfma_f32_32x32x16_bf16 v[82:97], v[230:233], v[98:101], v[82:97]
	v_mfma_f32_32x32x16_bf16 v[66:81], v[234:237], v[98:101], v[66:81]
	ds_read_b64_tr_b16 v[218:219], v194 offset:0x4000
	ds_read_b64_tr_b16 v[220:221], v194 offset:0x4800
	ds_read_b64_tr_b16 v[222:223], v194 offset:0x5000
	ds_read_b64_tr_b16 v[224:225], v194 offset:0x5800
	ds_read_b64_tr_b16 v[226:227], v194 offset:0x6000
	ds_read_b64_tr_b16 v[228:229], v194 offset:0x6800
	ds_read_b64_tr_b16 v[230:231], v194 offset:0x7000
	ds_read_b64_tr_b16 v[232:233], v194 offset:0x7800
	s_add_i32 s6, s82, 1
	s_cmp_lt_u32 s6, s83
	s_cselect_b64 s[90:91], -1, 0
	s_cmp_ge_u32 s6, s83
	s_cbranch_scc1 .LBB0_416
	s_add_u32 s8, s74, 0x1b98c000
	s_addc_u32 s9, s75, 0
	s_add_u32 s10, s74, 0x1b98e000
	s_addc_u32 s11, s75, 0
	s_add_u32 s12, s80, 0x18886000
	s_addc_u32 s13, s81, 0
	s_add_u32 s14, s74, 0x1d98c000
	s_addc_u32 s15, s75, 0
	s_add_u32 s16, s74, 0x1d98e000
	s_addc_u32 s17, s75, 0
	global_load_dwordx4 v[154:157], v201, s[8:9]
	global_load_dwordx4 v[158:161], v201, s[10:11]
	global_load_dwordx4 v[162:165], v199, s[12:13]
	global_load_dwordx4 v[146:149], v201, s[14:15]
	global_load_dwordx4 v[150:153], v201, s[16:17]
